# retention decay fully folded into q/k in the in-proj epilogue (gamma^pos, gamma^-pos/16 with absolute pos); per-tile gamma^(128*dchunk) scaling (exp + 16 mul per lane per tile) removed from the retent
# speedup vs baseline: 1.0042x; 1.0030x over previous
;     __device__ __forceinline__ void operator()(const Acc& acc, const Unit& u, int wr, int wc, int fr, int fq) const {
;     ...
;         const int type = u.pn >> 3, colt = (u.pn & 7) << 8, c8 = wc * 32 + 8 * fq, cp = wc * 64 + 8 * fq, lr0 = wr * 64 + fr;
;         const bool rot = (type == 2 || type == 3);
;         const float eh = __builtin_amdgcn_exp2f((float)(-5 - (u.pn & 7)));
;         const float lg2h = -(eh * (1.f + eh * (0.5f + eh * (0.33333334f + eh * (0.25f + eh * (0.2f + eh * 0.16666667f)))))) * 1.4426950408889634f;
;         f32x4 cur[4], nxt[4];
;         if (rot) { const f32x4* cs = (const f32x4*)(rope + ((size_t)((u.pm * 256 + lr0) & 2047) * 128 + c8) * 2);
; #pragma unroll
;             for (int j = 0; j < 4; ++j) cur[j] = cs[j]; }
; #pragma unroll
;         for (int idx = 0; idx < 8; ++idx) { const int ai = idx >> 2, m = idx & 3;
;                 const int lr = lr0 + ai * 128 + m * 16, r = u.pm * 256 + lr; const float s = rs[lr];
;                 if (rot && idx < 7) { const f32x4* cs = (const f32x4*)(rope + ((size_t)((u.pm * 256 + lr0 + ((idx + 1) >> 2) * 128 + ((idx + 1) & 3) * 16) & 2047) * 128 + c8) * 2);
.LBB0_144:
	v_lshl_add_u32 v0, v195, 2, 0
	v_add_u32_e32 v197, 0x26000, v0
	ds_read_b32 v166, v197
	s_lshl_b32 s78, s7, 8
	s_and_b32 s0, s78, 0x700
	s_or_b32 s1, s0, 0x80
	v_cndmask_b32_e64 v0, 0, 1, s[2:3]
	v_cmp_ne_u32_e64 s[36:37], 1, v0
	s_andn2_b64 vcc, exec, s[2:3]
	v_add_u32_e32 v170, s78, v195
	s_cbranch_vccnz .LBB0_146
	v_mov_b32_e32 v0, 0x800
	v_lshl_add_u32 v0, v170, 7, v0
	v_and_b32_e32 v0, 0x3ff80, v0
	v_lshl_add_u64 v[2:3], v[168:169], 0, v[0:1]
	v_lshl_add_u64 v[2:3], v[2:3], 3, s[54:55]
	global_load_dwordx4 v[14:17], v[2:3], off offset:48
	global_load_dwordx4 v[10:13], v[2:3], off offset:32
	global_load_dwordx4 v[6:9], v[2:3], off offset:16
	s_nop 0
	global_load_dwordx4 v[2:5], v[2:3], off

;     __device__ __forceinline__ void operator()(const Acc& acc, const Unit& u, int wr, int wc, int fr, int fq) const {
;     ...
;                 } else {
;                     const float sc = (type == 3) ? 0.0625f * __builtin_amdgcn_exp2f(-(float)(r & 127) * lg2h) : __builtin_amdgcn_exp2f((float)(r & 127) * lg2h);
;                     float o1[8], o2[8];
.LBB0_151:
	s_and_b64 vcc, exec, s[12:13]
	s_cbranch_vccz .LBB0_305
	v_and_b32_e32 v0, 0x7f, v195
	v_or_b32_e32 v0, s0, v0
	v_cvt_f32_u32_e32 v0, v0
	v_mul_f32_e64 v0, v196, -v0
	v_exp_f32_e32 v0, v0
	s_mov_b64 s[6:7], -1
	v_mul_f32_e32 v0, 0x3d800000, v0
	s_mov_b64 s[12:13], 0x2f000000
	s_branch .LBB0_155

;     __device__ __forceinline__ void operator()(const Acc& acc, const Unit& u, int wr, int wc, int fr, int fq) const {
;     ...
;                 } else {
;                     const float sc = (type == 3) ? 0.0625f * __builtin_amdgcn_exp2f(-(float)(r & 127) * lg2h) : __builtin_amdgcn_exp2f((float)(r & 127) * lg2h);
;                     float o1[8], o2[8];
.LBB0_155:
	s_andn2_b64 vcc, exec, s[38:39]
	s_cbranch_vccnz .LBB0_171
	v_and_b32_e32 v0, 0x7f, v195
	v_or_b32_e32 v0, s0, v0
	v_cvt_f32_u32_e32 v0, v0
	v_mul_f32_e32 v0, v196, v0
	v_exp_f32_e32 v0, v0
	s_mov_b64 s[4:5], 0
	v_ashrrev_i32_e32 v171, 31, v170
	s_branch .LBB0_172

;     __device__ __forceinline__ void operator()(const Acc& acc, const Unit& u, int wr, int wc, int fr, int fq) const {
;     ...
;                 } else {
;                     const float sc = (type == 3) ? 0.0625f * __builtin_amdgcn_exp2f(-(float)(r & 127) * lg2h) : __builtin_amdgcn_exp2f((float)(r & 127) * lg2h);
;                     float o1[8], o2[8];
.LBB0_169:
	s_and_b64 vcc, exec, s[4:5]
	s_cbranch_vccz .LBB0_306
	v_and_b32_e32 v18, 0x7f, v173
	v_or_b32_e32 v18, s0, v18
	v_cvt_f32_u32_e32 v18, v18
	v_mul_f32_e64 v18, v196, -v18
	v_exp_f32_e32 v18, v18
	s_mov_b64 s[6:7], -1
	v_mul_f32_e32 v167, 0x3d800000, v18
	s_mov_b64 s[4:5], 0x2f000000
	s_branch .LBB0_175

;     __device__ __forceinline__ void operator()(const Acc& acc, const Unit& u, int wr, int wc, int fr, int fq) const {
;     ...
;                 } else {
;                     const float sc = (type == 3) ? 0.0625f * __builtin_amdgcn_exp2f(-(float)(r & 127) * lg2h) : __builtin_amdgcn_exp2f((float)(r & 127) * lg2h);
;                     float o1[8], o2[8];
.LBB0_175:
	s_andn2_b64 vcc, exec, s[12:13]
	s_cbranch_vccnz .LBB0_191
	v_and_b32_e32 v18, 0x7f, v173
	v_or_b32_e32 v18, s0, v18
	v_cvt_f32_u32_e32 v18, v18
	v_mul_f32_e32 v18, v196, v18
	v_exp_f32_e32 v167, v18
	s_mov_b64 s[2:3], 0
	v_ashrrev_i32_e32 v173, 31, v172
	s_branch .LBB0_192

;     __device__ __forceinline__ void operator()(const Acc& acc, const Unit& u, int wr, int wc, int fr, int fq) const {
;     ...
;                 } else {
;                     const float sc = (type == 3) ? 0.0625f * __builtin_amdgcn_exp2f(-(float)(r & 127) * lg2h) : __builtin_amdgcn_exp2f((float)(r & 127) * lg2h);
;                     float o1[8], o2[8];
.LBB0_189:
	s_and_b64 vcc, exec, s[4:5]
	s_cbranch_vccz .LBB0_307
	v_and_b32_e32 v34, 0x7f, v149
	v_or_b32_e32 v34, s0, v34
	v_cvt_f32_u32_e32 v34, v34
	v_mul_f32_e64 v34, v196, -v34
	v_exp_f32_e32 v34, v34
	s_mov_b64 s[6:7], -1
	v_mul_f32_e32 v150, 0x3d800000, v34
	s_mov_b64 s[4:5], 0x2f000000
	s_branch .LBB0_195

;     __device__ __forceinline__ void operator()(const Acc& acc, const Unit& u, int wr, int wc, int fr, int fq) const {
;     ...
;                 } else {
;                     const float sc = (type == 3) ? 0.0625f * __builtin_amdgcn_exp2f(-(float)(r & 127) * lg2h) : __builtin_amdgcn_exp2f((float)(r & 127) * lg2h);
;                     float o1[8], o2[8];
.LBB0_195:
	s_andn2_b64 vcc, exec, s[12:13]
	s_cbranch_vccnz .LBB0_211
	v_and_b32_e32 v34, 0x7f, v149
	v_or_b32_e32 v34, s0, v34
	v_cvt_f32_u32_e32 v34, v34
	v_mul_f32_e32 v34, v196, v34
	v_exp_f32_e32 v150, v34
	s_mov_b64 s[2:3], 0
	v_ashrrev_i32_e32 v149, 31, v148
	s_branch .LBB0_212

;     __device__ __forceinline__ void operator()(const Acc& acc, const Unit& u, int wr, int wc, int fr, int fq) const {
;     ...
;                 } else {
;                     const float sc = (type == 3) ? 0.0625f * __builtin_amdgcn_exp2f(-(float)(r & 127) * lg2h) : __builtin_amdgcn_exp2f((float)(r & 127) * lg2h);
;                     float o1[8], o2[8];
.LBB0_209:
	s_and_b64 vcc, exec, s[4:5]
	s_cbranch_vccz .LBB0_308
	v_and_b32_e32 v50, 0x7f, v31
	v_or_b32_e32 v50, s0, v50
	v_cvt_f32_u32_e32 v50, v50
	v_mul_f32_e64 v50, v196, -v50
	v_exp_f32_e32 v50, v50
	s_mov_b64 s[6:7], -1
	v_mul_f32_e32 v134, 0x3d800000, v50
	s_mov_b64 s[4:5], 0x2f000000
	s_branch .LBB0_215

;     __device__ __forceinline__ void operator()(const Acc& acc, const Unit& u, int wr, int wc, int fr, int fq) const {
;     ...
;                 } else {
;                     const float sc = (type == 3) ? 0.0625f * __builtin_amdgcn_exp2f(-(float)(r & 127) * lg2h) : __builtin_amdgcn_exp2f((float)(r & 127) * lg2h);
;                     float o1[8], o2[8];
.LBB0_215:
	s_andn2_b64 vcc, exec, s[12:13]
	s_cbranch_vccnz .LBB0_231
	v_and_b32_e32 v31, 0x7f, v31
	v_or_b32_e32 v31, s0, v31
	v_cvt_f32_u32_e32 v31, v31
	v_mul_f32_e32 v31, v196, v31
	v_exp_f32_e32 v134, v31
	s_mov_b64 s[2:3], 0
	v_ashrrev_i32_e32 v31, 31, v30
	s_branch .LBB0_232

;     __device__ __forceinline__ void operator()(const Acc& acc, const Unit& u, int wr, int wc, int fr, int fq) const {
;     ...
;                 } else {
;                     const float sc = (type == 3) ? 0.0625f * __builtin_amdgcn_exp2f(-(float)(r & 127) * lg2h) : __builtin_amdgcn_exp2f((float)(r & 127) * lg2h);
;                     float o1[8], o2[8];
.LBB0_229:
	s_and_b64 vcc, exec, s[4:5]
	s_cbranch_vccz .LBB0_309
	v_and_b32_e32 v18, 0x7f, v195
	v_or_b32_e32 v18, s1, v18
	v_cvt_f32_u32_e32 v18, v18
	v_mul_f32_e64 v18, v196, -v18
	v_exp_f32_e32 v18, v18
	s_mov_b64 s[6:7], -1
	v_mul_f32_e32 v116, 0x3d800000, v18
	s_mov_b64 s[4:5], 0x2f000000
	s_branch .LBB0_235

;     __device__ __forceinline__ void operator()(const Acc& acc, const Unit& u, int wr, int wc, int fr, int fq) const {
;     ...
;                 } else {
;                     const float sc = (type == 3) ? 0.0625f * __builtin_amdgcn_exp2f(-(float)(r & 127) * lg2h) : __builtin_amdgcn_exp2f((float)(r & 127) * lg2h);
;                     float o1[8], o2[8];
.LBB0_235:
	s_andn2_b64 vcc, exec, s[12:13]
	s_cbranch_vccnz .LBB0_251
	v_and_b32_e32 v18, 0x7f, v195
	v_or_b32_e32 v18, s1, v18
	v_cvt_f32_u32_e32 v18, v18
	v_mul_f32_e32 v18, v196, v18
	v_exp_f32_e32 v116, v18
	s_mov_b64 s[2:3], 0
	v_ashrrev_i32_e32 v47, 31, v46
	s_branch .LBB0_252

;     __device__ __forceinline__ void operator()(const Acc& acc, const Unit& u, int wr, int wc, int fr, int fq) const {
;     ...
;                 } else {
;                     const float sc = (type == 3) ? 0.0625f * __builtin_amdgcn_exp2f(-(float)(r & 127) * lg2h) : __builtin_amdgcn_exp2f((float)(r & 127) * lg2h);
;                     float o1[8], o2[8];
.LBB0_249:
	s_and_b64 vcc, exec, s[4:5]
	s_cbranch_vccz .LBB0_310
	v_and_b32_e32 v34, 0x7f, v63
	v_or_b32_e32 v34, s1, v34
	v_cvt_f32_u32_e32 v34, v34
	v_mul_f32_e64 v34, v196, -v34
	v_exp_f32_e32 v34, v34
	s_mov_b64 s[6:7], -1
	v_mul_f32_e32 v98, 0x3d800000, v34
	s_mov_b64 s[4:5], 0x2f000000
	s_branch .LBB0_255

;     __device__ __forceinline__ void operator()(const Acc& acc, const Unit& u, int wr, int wc, int fr, int fq) const {
;     ...
;                 } else {
;                     const float sc = (type == 3) ? 0.0625f * __builtin_amdgcn_exp2f(-(float)(r & 127) * lg2h) : __builtin_amdgcn_exp2f((float)(r & 127) * lg2h);
;                     float o1[8], o2[8];
.LBB0_255:
	s_andn2_b64 vcc, exec, s[12:13]
	s_cbranch_vccnz .LBB0_271
	v_and_b32_e32 v34, 0x7f, v63
	v_or_b32_e32 v34, s1, v34
	v_cvt_f32_u32_e32 v34, v34
	v_mul_f32_e32 v34, v196, v34
	v_exp_f32_e32 v98, v34
	s_mov_b64 s[2:3], 0
	v_ashrrev_i32_e32 v63, 31, v62
	s_branch .LBB0_272

;     __device__ __forceinline__ void operator()(const Acc& acc, const Unit& u, int wr, int wc, int fr, int fq) const {
;     ...
;                 } else {
;                     const float sc = (type == 3) ? 0.0625f * __builtin_amdgcn_exp2f(-(float)(r & 127) * lg2h) : __builtin_amdgcn_exp2f((float)(r & 127) * lg2h);
;                     float o1[8], o2[8];
.LBB0_269:
	s_and_b64 vcc, exec, s[4:5]
	s_cbranch_vccz .LBB0_311
	v_and_b32_e32 v52, 0x7f, v31
	v_or_b32_e32 v52, s1, v52
	v_cvt_f32_u32_e32 v52, v52
	v_mul_f32_e64 v52, v196, -v52
	v_exp_f32_e32 v52, v52
	s_mov_b64 s[6:7], -1
	v_mul_f32_e32 v52, 0x3d800000, v52
	s_mov_b64 s[4:5], 0x2f000000
	s_branch .LBB0_275

;     __device__ __forceinline__ void operator()(const Acc& acc, const Unit& u, int wr, int wc, int fr, int fq) const {
;     ...
;                 } else {
;                     const float sc = (type == 3) ? 0.0625f * __builtin_amdgcn_exp2f(-(float)(r & 127) * lg2h) : __builtin_amdgcn_exp2f((float)(r & 127) * lg2h);
;                     float o1[8], o2[8];
.LBB0_275:
	s_andn2_b64 vcc, exec, s[12:13]
	s_cbranch_vccnz .LBB0_289
	v_and_b32_e32 v31, 0x7f, v31
	v_or_b32_e32 v31, s1, v31
	v_cvt_f32_u32_e32 v31, v31
	v_mul_f32_e32 v31, v196, v31
	v_exp_f32_e32 v52, v31
	s_mov_b64 s[2:3], 0
	v_ashrrev_i32_e32 v31, 31, v30
	s_branch .LBB0_290

;     __device__ __forceinline__ void operator()(const Acc& acc, const Unit& u, int wr, int wc, int fr, int fq) const {
;     ...
;                 } else {
;                     const float sc = (type == 3) ? 0.0625f * __builtin_amdgcn_exp2f(-(float)(r & 127) * lg2h) : __builtin_amdgcn_exp2f((float)(r & 127) * lg2h);
;                     float o1[8], o2[8];
.LBB0_287:
	s_and_b64 vcc, exec, s[4:5]
	s_cbranch_vccz .LBB0_312
	v_and_b32_e32 v36, 0x7f, v31
	v_or_b32_e32 v36, s1, v36
	v_cvt_f32_u32_e32 v36, v36
	v_mul_f32_e64 v36, v196, -v36
	v_exp_f32_e32 v36, v36
	s_mov_b64 s[6:7], -1
	v_mul_f32_e32 v36, 0x3d800000, v36
	s_mov_b64 s[4:5], 0x2f000000
	s_branch .LBB0_293

;     __device__ __forceinline__ void operator()(const Acc& acc, const Unit& u, int wr, int wc, int fr, int fq) const {
;     ...
;                 } else {
;                     const float sc = (type == 3) ? 0.0625f * __builtin_amdgcn_exp2f(-(float)(r & 127) * lg2h) : __builtin_amdgcn_exp2f((float)(r & 127) * lg2h);
;                     float o1[8], o2[8];
.LBB0_293:
	s_andn2_b64 vcc, exec, s[12:13]
	s_cbranch_vccnz .LBB0_303
	v_and_b32_e32 v31, 0x7f, v31
	v_or_b32_e32 v31, s1, v31
	v_cvt_f32_u32_e32 v31, v31
	v_mul_f32_e32 v31, v196, v31
	v_exp_f32_e32 v36, v31
	s_mov_b64 s[2:3], 0
	v_ashrrev_i32_e32 v31, 31, v30
	s_branch .LBB0_304

; __device__ __forceinline__ unsigned cvt_pk_bf16(float lo, float hi) { unsigned r; asm volatile("v_cvt_pk_bf16_f32 %0, %1, %2" : "=v"(r) : "v"(lo), "v"(hi)); return r; }
; __device__ __forceinline__ void p2_ret(const Frame& F, ArgsP a, int layer) {
;     ...
;                 { const bool diag = kt >= 2 * qi;
;                   unsigned pk[8];
;                   if (!diag) { const float tf = __builtin_amdgcn_exp2f((float)(128 * (qi - (kt >> 1))) * lg2);
; #pragma unroll
;                       for (int i = 0; i < 8; ++i) pk[i] = cvt_pk_bf16(st[2 * i] * tf, st[2 * i + 1] * tf);
.LBB0_385:
	s_andn2_b64 vcc, exec, s[4:5]
	s_cbranch_vccnz .LBB0_387
	v_cvt_pk_bf16_f32 v190, v98, v99
	v_cvt_pk_bf16_f32 v191, v100, v101
	v_cvt_pk_bf16_f32 v192, v102, v103
	v_cvt_pk_bf16_f32 v193, v104, v105
	v_cvt_pk_bf16_f32 v194, v106, v107
	v_cvt_pk_bf16_f32 v195, v108, v109
	v_cvt_pk_bf16_f32 v196, v110, v111
	v_cvt_pk_bf16_f32 v197, v112, v113
